# proj GEMM: XCD-compact tile mapping (each XCD owns 16 m-tiles; 4 blocks of an XCD share an A tile)
# baseline (speedup 1.0000x reference)
.LBB0_6:
	s_load_dwordx16 s[36:51], s[0:1], 0x0
	s_cmp_eq_u32 s28, 0
	s_load_dwordx16 s[76:91], s[0:1], 0xc0
	s_mul_i32 s6, s19, s18
	s_mov_b32 s4, s28
	s_waitcnt lgkmcnt(0)
	v_writelane_b32 v250, s36, 2
	s_mul_i32 s6, s6, s9
	s_mov_b32 s71, 0x30000
	v_writelane_b32 v250, s37, 3
	v_writelane_b32 v250, s38, 4
	v_writelane_b32 v250, s39, 5
	v_writelane_b32 v250, s40, 6
	v_writelane_b32 v250, s41, 7
	v_writelane_b32 v250, s42, 8
	v_writelane_b32 v250, s43, 9
	v_writelane_b32 v250, s44, 10
	v_writelane_b32 v250, s45, 11
	v_writelane_b32 v250, s46, 12
	v_writelane_b32 v250, s47, 13
	v_writelane_b32 v250, s48, 14
	v_writelane_b32 v250, s49, 15
	v_writelane_b32 v250, s50, 16
	v_writelane_b32 v250, s51, 17
	s_load_dwordx16 s[36:51], s[0:1], 0x40
	s_load_dwordx16 s[52:67], s[0:1], 0x80
	s_cselect_b64 s[0:1], -1, 0
	s_movk_i32 s33, 0x4000
	v_mov_b32_e32 v213, 0x358637bd
	s_mov_b32 s35, 0x10885000
	s_waitcnt lgkmcnt(0)
	v_writelane_b32 v250, s52, 18
	v_mov_b32_e32 v220, 0x121f0
	s_mov_b32 s69, 0x42ee0000
	v_writelane_b32 v250, s53, 19
	v_writelane_b32 v250, s54, 20
	v_writelane_b32 v250, s55, 21
	v_writelane_b32 v250, s56, 22
	v_writelane_b32 v250, s57, 23
	v_writelane_b32 v250, s58, 24
	v_writelane_b32 v250, s59, 25
	v_writelane_b32 v250, s60, 26
	v_writelane_b32 v250, s61, 27
	v_writelane_b32 v250, s62, 28
	v_writelane_b32 v250, s63, 29
	v_writelane_b32 v250, s64, 30
	v_writelane_b32 v250, s65, 31
	v_writelane_b32 v250, s66, 32
	v_writelane_b32 v250, s67, 33
	v_writelane_b32 v250, s0, 34
	s_mov_b32 s57, 0
	s_mov_b32 s19, s57
	v_writelane_b32 v250, s1, 35
	s_add_u32 s0, s94, 0x9885000
	s_addc_u32 s1, s95, 0
	v_writelane_b32 v250, s0, 36
	s_cmpk_lt_i32 s28, 0x180
	s_mov_b32 s29, s57
	v_writelane_b32 v250, s1, 37
	s_cselect_b64 s[0:1], -1, 0
	v_writelane_b32 v250, s0, 38
	s_mov_b32 s55, 0x20000
	s_movk_i32 s67, 0x6000
	v_writelane_b32 v250, s1, 39
	s_add_u32 s0, s94, 0x9660000
	s_addc_u32 s1, s95, 0
	v_writelane_b32 v250, s0, 40
	s_cmpk_lt_i32 s28, 0x280
	s_mov_b32 s54, 0x800000
	v_writelane_b32 v250, s1, 41
	s_cselect_b64 s[0:1], -1, 0
	v_writelane_b32 v250, s0, 42
	s_movk_i32 s61, 0x3fff
	s_mov_b32 s58, 0x3e8293ee
	v_writelane_b32 v250, s1, 43
	s_add_u32 s0, s94, 0x188c9100
	v_writelane_b32 v250, s0, 44
	s_addc_u32 s0, s95, 0
	v_writelane_b32 v250, s0, 45
	s_lshl_b64 s[0:1], s[18:19], 8
	v_writelane_b32 v250, s0, 46
	v_mov_b32_e32 v221, 0xff800000
	v_mov_b32_e32 v222, 0x80
	v_writelane_b32 v250, s1, 47
	s_lshl_b64 s[0:1], s[28:29], 8
	v_writelane_b32 v250, s0, 48
	v_mov_b32_e32 v223, 0x800
	v_mov_b32_e32 v224, 0x8000
	v_writelane_b32 v250, s1, 49
	s_add_u32 s0, s94, 0x1600000
	v_writelane_b32 v250, s0, 50
	s_addc_u32 s0, s95, 0
	v_writelane_b32 v250, s0, 51
	s_add_u32 s0, s94, 0x1620000
	s_addc_u32 s1, s95, 0
	v_writelane_b32 v250, s0, 52
	s_ashr_i32 s5, s28, 31
	s_lshl_b64 s[10:11], s[4:5], 8
	v_writelane_b32 v250, s1, 53
	s_ashr_i32 s1, s18, 31
	s_mov_b32 s0, s18
	s_lshl_b64 s[22:23], s[0:1], 8
	v_writelane_b32 v250, s10, 54
	s_add_u32 s7, s94, 0x9685000
	v_mov_b32_e32 v225, 0x80000
	v_writelane_b32 v250, s11, 55
	v_writelane_b32 v250, s7, 56
	s_addc_u32 s7, s95, 0
	s_add_u32 s14, s94, 0x9705000
	s_addc_u32 s15, s95, 0
	v_writelane_b32 v250, s7, 57
	s_add_u32 s7, s94, 0x9785000
	v_writelane_b32 v250, s7, 58
	s_addc_u32 s7, s95, 0
	s_add_u32 s16, s94, 0x9805000
	s_addc_u32 s17, s95, 0
	s_cmp_gt_i32 s18, 1
	s_cselect_b64 s[10:11], -1, 0
	v_cndmask_b32_e64 v1, 0, 1, s[10:11]
	v_writelane_b32 v250, s7, 59
	v_readfirstlane_b32 s7, v1
	s_cmp_eq_u32 s28, s7
	s_cselect_b64 s[10:11], -1, 0
	s_add_u32 s24, s94, 0x9684000
	v_writelane_b32 v250, s10, 60
	s_addc_u32 s25, s95, 0
	v_lshrrev_b32_e32 v1, 20, v0
	v_writelane_b32 v250, s11, 61
	s_add_u32 s10, s94, 0x9885100
	s_addc_u32 s11, s95, 0
	v_writelane_b32 v250, s10, 62
	v_lshrrev_b32_e32 v0, 10, v0
	v_or_b32_e32 v0, v0, v1
	v_writelane_b32 v250, s11, 63
	s_lshl_b64 s[10:11], s[28:29], 14
	s_add_u32 s7, s94, s10
	s_addc_u32 s10, s95, s11
	s_add_u32 s26, s7, 0x17885100
	s_addc_u32 s27, s10, 0
	v_writelane_b32 v251, s26, 0
	s_cmpk_lt_i32 s28, 0x400
	s_cselect_b64 s[10:11], -1, 0
	v_writelane_b32 v251, s27, 1
	v_writelane_b32 v251, s10, 2
	s_add_u32 s7, s94, 0xe00000
	s_mov_b64 s[62:63], s[24:25]
	v_writelane_b32 v251, s11, 3
	v_writelane_b32 v251, s7, 4
	s_addc_u32 s7, s95, 0
	v_writelane_b32 v251, s7, 5
	s_lshl_b32 s7, s28, 8
	s_and_b32 s7, s7, 0x700
	v_writelane_b32 v251, s7, 6
	s_lshl_b32 s7, s28, 4
	v_writelane_b32 v251, s7, 7
	s_and_b32 s7, s7, 0xffffff80
	s_add_u32 s10, s94, 0x16885100
	v_writelane_b32 v251, s7, 8
	s_addc_u32 s11, s95, 0
	v_writelane_b32 v251, s10, 9
	v_mov_b32_e32 v1, 0
	v_mov_b32_e32 v226, 0x800000
	v_writelane_b32 v251, s11, 10
	s_add_u32 s10, s94, 0x17085100
	s_addc_u32 s11, s95, 0
	v_writelane_b32 v251, s10, 11
	s_lshl_b32 s59, s18, 2
	s_lshl_b32 s12, s18, 4
	v_writelane_b32 v251, s11, 12
	s_lshl_b32 s11, s28, 2
	s_add_u32 s26, s94, 0x12885100
	s_addc_u32 s27, s95, 0
	v_writelane_b32 v251, s26, 13
	v_bfrev_b32_e32 v227, 16
	s_nop 0
	v_writelane_b32 v251, s27, 14
	s_add_u32 s26, s94, 0x10885100
	s_addc_u32 s27, s95, 0
	v_writelane_b32 v251, s26, 15
	s_add_u32 s7, s94, 0xa00000
	s_nop 0
	v_writelane_b32 v251, s27, 16
	v_writelane_b32 v251, s7, 17
	s_addc_u32 s7, s95, 0
	v_writelane_b32 v251, s7, 18
	s_lshl_b32 s7, s28, 7
	v_writelane_b32 v251, s7, 19
	s_and_b32 s7, s7, 0x380
	s_add_u32 s26, s94, 0xb885100
	v_writelane_b32 v251, s7, 20
	s_addc_u32 s27, s95, 0
	v_writelane_b32 v251, s26, 21
	s_nop 1
	v_writelane_b32 v251, s27, 22
	s_add_u32 s26, s94, 0xc085100
	s_addc_u32 s27, s95, 0
	v_writelane_b32 v251, s26, 23
	s_nop 1
	v_writelane_b32 v251, s27, 24
	s_add_u32 s26, s94, 0x10085100
	s_addc_u32 s27, s95, 0
	v_writelane_b32 v251, s26, 25
	s_add_u32 s7, s94, 0xf885100
	s_nop 0
	v_writelane_b32 v251, s27, 26
	v_writelane_b32 v251, s7, 27
	s_addc_u32 s7, s95, 0
	v_writelane_b32 v251, s7, 28
	s_add_u32 s7, s94, 0xc885100
	v_writelane_b32 v251, s7, 29
	s_addc_u32 s7, s95, 0
	v_writelane_b32 v251, s7, 30
	s_add_u32 s7, s94, 0xd085100
	v_writelane_b32 v251, s7, 31
	s_addc_u32 s7, s95, 0
	v_writelane_b32 v251, s7, 32
	s_add_u32 s7, s94, 0xd885100
	v_writelane_b32 v251, s7, 33
	s_addc_u32 s7, s95, 0
	v_writelane_b32 v251, s7, 34
	s_add_u32 s7, s94, 0xe085100
	v_writelane_b32 v251, s7, 35
	s_addc_u32 s7, s95, 0
	v_writelane_b32 v251, s7, 36
	s_add_u32 s7, s94, 0xe885100
	v_writelane_b32 v251, s7, 37
	s_addc_u32 s7, s95, 0
	v_writelane_b32 v251, s7, 38
	s_add_u32 s7, s94, 0xf085100
	v_writelane_b32 v251, s7, 39
	s_addc_u32 s7, s95, 0
	v_writelane_b32 v251, s7, 40
	s_add_u32 s7, s94, 0xcc85100
	v_writelane_b32 v251, s7, 41
	s_addc_u32 s7, s95, 0
	v_writelane_b32 v251, s7, 42
	s_add_u32 s7, s94, 0xe485100
	v_writelane_b32 v251, s7, 43
	s_addc_u32 s7, s95, 0
	v_writelane_b32 v251, s7, 44
	s_add_u32 s7, s94, 0xec85100
	v_writelane_b32 v251, s7, 45
	s_addc_u32 s7, s95, 0
	v_writelane_b32 v251, s7, 46
	s_add_u32 s7, s94, 0xf485100
	v_writelane_b32 v251, s7, 47
	s_addc_u32 s7, s95, 0
	v_writelane_b32 v251, s7, 48
	s_cmpk_lt_i32 s28, 0xa00
	s_cselect_b64 s[26:27], -1, 0
	s_and_b32 s7, s28, 7
	s_lshl_b32 s7, s7, 4
	s_bfe_u32 s98, s28, 0x40004
	s_add_u32 s7, s7, s98
	s_lshr_b32 s10, s28, 9
	s_lshl_b32 s10, s10, 2
	s_bfe_u32 s98, s28, 0x10003
	s_add_u32 s10, s10, s98
	s_bfe_u32 s98, s28, 0x10008
	s_lshl_b32 s98, s98, 1
	s_add_u32 s10, s10, s98
	v_writelane_b32 v251, s26, 49
	s_lshl_b32 s10, s10, 7
	v_writelane_b32 v251, s27, 50
	s_lshl_b32 s7, s7, 7
	v_writelane_b32 v251, s10, 51
	s_add_u32 s26, s90, 0x4000000
	v_writelane_b32 v251, s7, 52
	s_addc_u32 s27, s91, 0
	v_writelane_b32 v251, s26, 53
	s_nop 1
	v_writelane_b32 v251, s27, 54
	s_add_u32 s26, s90, 0x6000000
	s_addc_u32 s27, s91, 0
	v_writelane_b32 v251, s26, 55
	s_add_u32 s7, s94, 0x1660000
	s_nop 0
	v_writelane_b32 v251, s27, 56
	v_writelane_b32 v251, s7, 57
	s_addc_u32 s7, s95, 0
	v_writelane_b32 v251, s7, 58
	s_add_u32 s7, s94, 0x5660000
	v_writelane_b32 v251, s7, 59
	s_addc_u32 s7, s95, 0
	v_writelane_b32 v251, s7, 60
	s_add_u32 s7, s94, 0x18885100
	v_writelane_b32 v251, s7, 61
	s_addc_u32 s7, s95, 0
	v_writelane_b32 v251, s7, 62
	s_add_u32 s7, s94, 0x188a5100
	v_writelane_b32 v251, s7, 63
	s_addc_u32 s7, s95, 0
	v_writelane_b32 v252, s7, 0
	s_lshl_b32 s7, s18, 5
	v_writelane_b32 v252, s7, 1
	s_add_u32 s26, s36, 0x1000
	v_writelane_b32 v252, s36, 2
	s_addc_u32 s27, s37, 0
	s_nop 0
	v_writelane_b32 v252, s37, 3
	v_writelane_b32 v252, s38, 4
	v_writelane_b32 v252, s39, 5
	v_writelane_b32 v252, s40, 6
	v_writelane_b32 v252, s41, 7
	v_writelane_b32 v252, s42, 8
	v_writelane_b32 v252, s43, 9
	v_writelane_b32 v252, s44, 10
	v_writelane_b32 v252, s45, 11
	v_writelane_b32 v252, s46, 12
	v_writelane_b32 v252, s47, 13
	v_writelane_b32 v252, s48, 14
	v_writelane_b32 v252, s49, 15
	v_writelane_b32 v252, s50, 16
	v_writelane_b32 v252, s51, 17
	v_writelane_b32 v252, s26, 18
	v_readlane_b32 s36, v250, 2
	v_readlane_b32 s48, v250, 14
	v_writelane_b32 v252, s27, 19
	v_writelane_b32 v252, s6, 20
	s_add_u32 s6, s94, 0x188c5300
	s_addc_u32 s7, s95, 0
	v_writelane_b32 v252, s6, 21
	v_readlane_b32 s49, v250, 15
	v_readlane_b32 s50, v250, 16
	v_writelane_b32 v252, s7, 22
	s_add_u32 s6, s94, 0x188c5500
	s_addc_u32 s7, s95, 0
	v_writelane_b32 v252, s6, 23
	v_readlane_b32 s51, v250, 17
	s_mov_b64 s[50:51], s[30:31]
	v_writelane_b32 v252, s7, 24
	s_add_u32 s6, s94, 0x188c5600
	s_addc_u32 s7, s95, 0
	v_writelane_b32 v252, s6, 25
	v_readlane_b32 s37, v250, 3
	v_readlane_b32 s38, v250, 4
	v_writelane_b32 v252, s7, 26
	s_add_u32 s6, s94, 0x188c5700
	s_addc_u32 s7, s95, 0
	v_writelane_b32 v252, s6, 27
	s_movk_i32 s36, 0xff
	s_movk_i32 s37, 0x7fff
	v_writelane_b32 v252, s7, 28
	s_add_u32 s6, s94, 0x188c5800
	s_addc_u32 s7, s95, 0
	v_writelane_b32 v252, s6, 29
	s_movk_i32 s38, 0x2800
	v_readlane_b32 s39, v250, 5
	v_writelane_b32 v252, s7, 30
	s_add_u32 s6, s94, 0x188c5900
	s_addc_u32 s7, s95, 0
	v_writelane_b32 v252, s6, 31
	v_readlane_b32 s40, v250, 6
	v_readlane_b32 s41, v250, 7
	v_writelane_b32 v252, s7, 32
	s_add_u32 s6, s94, 0x188c5a00
	s_addc_u32 s7, s95, 0
	v_writelane_b32 v252, s6, 33
	v_readlane_b32 s42, v250, 8
	v_readlane_b32 s43, v250, 9
	v_writelane_b32 v252, s7, 34
	s_add_u32 s6, s94, 0x188c5b00
	s_addc_u32 s7, s95, 0
	v_writelane_b32 v252, s6, 35
	v_readlane_b32 s44, v250, 10
	v_readlane_b32 s45, v250, 11
	v_writelane_b32 v252, s7, 36
	s_add_u32 s6, s94, 0x188c5c00
	s_addc_u32 s7, s95, 0
	v_writelane_b32 v252, s6, 37
	v_readlane_b32 s46, v250, 12
	v_readlane_b32 s47, v250, 13
	v_writelane_b32 v252, s7, 38
	s_add_u32 s6, s94, 0x188c5d00
	s_addc_u32 s7, s95, 0
	v_writelane_b32 v252, s6, 39
	s_nop 1
	v_writelane_b32 v252, s7, 40
	s_add_u32 s6, s94, 0x188c5e00
	s_addc_u32 s7, s95, 0
	v_writelane_b32 v252, s6, 41
	s_nop 1
	v_writelane_b32 v252, s7, 42
	s_add_u32 s6, s94, 0x188c5f00
	s_addc_u32 s7, s95, 0
	v_writelane_b32 v252, s6, 43
	s_nop 1
	v_writelane_b32 v252, s7, 44
	s_add_u32 s6, s94, 0x188c6000
	s_addc_u32 s7, s95, 0
	v_writelane_b32 v252, s6, 45
	s_nop 1
	v_writelane_b32 v252, s7, 46
	s_add_u32 s6, s94, 0x188c6100
	s_addc_u32 s7, s95, 0
	v_writelane_b32 v252, s6, 47
	s_nop 1
	v_writelane_b32 v252, s7, 48
	s_add_u32 s6, s94, 0x188c6200
	s_addc_u32 s7, s95, 0
	v_writelane_b32 v252, s6, 49
	s_nop 1
	v_writelane_b32 v252, s7, 50
	s_add_u32 s6, s94, 0x188c6300
	s_addc_u32 s7, s95, 0
	v_writelane_b32 v252, s6, 51
	s_nop 1
	v_writelane_b32 v252, s7, 52
	s_add_u32 s6, s94, 0x188c6400
	s_addc_u32 s7, s95, 0
	v_writelane_b32 v252, s6, 53
	s_cmp_eq_u32 s8, 15
	s_nop 0
	v_writelane_b32 v252, s7, 54
	s_cselect_b64 s[6:7], -1, 0
	v_writelane_b32 v252, s6, 55
	s_cmp_eq_u32 s8, 14
	s_nop 0
	v_writelane_b32 v252, s7, 56
	s_cselect_b64 s[6:7], -1, 0
	v_writelane_b32 v252, s6, 57
	s_cmp_eq_u32 s8, 13
	s_nop 0
	v_writelane_b32 v252, s7, 58
	s_cselect_b64 s[6:7], -1, 0
	v_writelane_b32 v252, s6, 59
	s_cmp_eq_u32 s8, 12
	s_nop 0
	v_writelane_b32 v252, s7, 60
	s_cselect_b64 s[6:7], -1, 0
	v_writelane_b32 v252, s6, 61
	s_cmp_eq_u32 s8, 11
	s_nop 0
	v_writelane_b32 v252, s7, 62
	s_cselect_b64 s[6:7], -1, 0
	v_writelane_b32 v252, s6, 63
	s_cmp_eq_u32 s8, 10
	s_nop 0
	v_writelane_b32 v253, s7, 0
	s_cselect_b64 s[6:7], -1, 0
	v_writelane_b32 v253, s6, 1
	s_cmp_eq_u32 s8, 9
	s_nop 0
	v_writelane_b32 v253, s7, 2
	s_cselect_b64 s[6:7], -1, 0
	v_writelane_b32 v253, s6, 3
	s_cmp_eq_u32 s8, 8
	s_nop 0
	v_writelane_b32 v253, s7, 4
	s_cselect_b64 s[6:7], -1, 0
	v_writelane_b32 v253, s6, 5
	s_cmp_eq_u32 s8, 7
	s_nop 0
	v_writelane_b32 v253, s7, 6
	s_cselect_b64 s[6:7], -1, 0
	v_writelane_b32 v253, s6, 7
	s_cmp_eq_u32 s8, 6
	s_nop 0
	v_writelane_b32 v253, s7, 8
	s_cselect_b64 s[6:7], -1, 0
	v_writelane_b32 v253, s6, 9
	s_cmp_eq_u32 s8, 5
	s_nop 0
	v_writelane_b32 v253, s7, 10
	s_cselect_b64 s[6:7], -1, 0
	v_writelane_b32 v253, s6, 11
	s_cmp_eq_u32 s8, 4
	s_nop 0
	v_writelane_b32 v253, s7, 12
	s_cselect_b64 s[6:7], -1, 0
	v_writelane_b32 v253, s6, 13
	s_cmp_eq_u32 s8, 3
	s_nop 0
	v_writelane_b32 v253, s7, 14
	s_cselect_b64 s[6:7], -1, 0
	v_writelane_b32 v253, s6, 15
	s_cmp_eq_u32 s8, 2
	s_nop 0
	v_writelane_b32 v253, s7, 16
	s_cselect_b64 s[6:7], -1, 0
	v_writelane_b32 v253, s6, 17
	s_cmp_eq_u32 s8, 1
	s_nop 0
	v_writelane_b32 v253, s7, 18
	s_cselect_b64 s[6:7], -1, 0
	v_writelane_b32 v253, s6, 19
	s_cmp_eq_u32 s8, 0
	s_nop 0
	v_writelane_b32 v253, s7, 20
	s_cselect_b64 s[6:7], -1, 0
	v_writelane_b32 v253, s6, 21
	s_nop 1
	v_writelane_b32 v253, s7, 22
	s_lshl_b32 s6, s8, 8
	s_add_u32 s2, s2, s6
	s_addc_u32 s3, s3, 0
	s_add_u32 s6, s2, 0x1400
	s_addc_u32 s7, s3, 0
	v_writelane_b32 v253, s6, 23
	s_add_u32 s2, s2, 0x2400
	s_addc_u32 s3, s3, 0
	v_writelane_b32 v253, s7, 24
	v_writelane_b32 v253, s2, 25
	s_nop 1
	v_writelane_b32 v253, s3, 26
	s_add_u32 s2, s94, 0x188c8500
	s_addc_u32 s3, s95, 0
	v_writelane_b32 v253, s2, 27
	s_nop 1
	v_writelane_b32 v253, s3, 28
	s_add_u32 s2, s94, 0x188c8600
	s_addc_u32 s3, s95, 0
	v_writelane_b32 v253, s2, 29
	s_cmp_lt_i32 s21, 0
	s_nop 0
	v_writelane_b32 v253, s3, 30
	s_cselect_b64 s[2:3], -1, 0
	v_writelane_b32 v253, s2, 31
	s_nop 1
	v_writelane_b32 v253, s3, 32
	s_movk_i32 s2, 0x3ff
	v_and_or_b32 v0, v0, s2, v218
	v_cmp_eq_u32_e64 s[2:3], 0, v0
	v_mbcnt_lo_u32_b32 v0, -1, 0
	v_mbcnt_hi_u32_b32 v219, -1, v0
	v_writelane_b32 v253, s2, 33
	s_nop 1
	v_writelane_b32 v253, s3, 34
	s_add_u32 s2, s48, 0x5a000
	s_addc_u32 s3, s49, 0
	v_writelane_b32 v253, s2, 35
	s_nop 1
	v_writelane_b32 v253, s3, 36
	s_lshl_b64 s[2:3], s[28:29], 12
	s_add_u32 s6, s94, s2
	s_addc_u32 s7, s95, s3
	s_add_u32 s2, s6, 0x188c9100
	s_addc_u32 s3, s7, 0
	v_writelane_b32 v253, s2, 37
	s_lshl_b64 s[64:65], s[18:19], 12
	s_mov_b64 s[96:97], s[64:65]
	v_writelane_b32 v253, s3, 38
	s_mov_b32 s2, s28
	v_writelane_b32 v253, s2, 39
	s_nop 1
	v_writelane_b32 v253, s3, 40
	s_lshl_b64 s[2:3], s[28:29], 13
	s_or_b32 s2, s2, 16
	s_add_u32 s8, s82, s2
	s_addc_u32 s9, s83, s3
	v_writelane_b32 v253, s8, 41
	s_nop 1
	v_writelane_b32 v253, s9, 42
	s_lshl_b64 s[8:9], s[18:19], 13
	v_writelane_b32 v253, s8, 43
	s_nop 1
	v_writelane_b32 v253, s9, 44
	s_add_u32 s8, s6, 0x1600000
	s_addc_u32 s9, s7, 0
	v_writelane_b32 v253, s8, 45
	s_nop 1
	v_writelane_b32 v253, s9, 46
	s_add_u32 s8, s84, s2
	s_addc_u32 s9, s85, s3
	v_writelane_b32 v253, s8, 47
	s_add_u32 s6, s6, 0x1620000
	s_addc_u32 s7, s7, 0
	v_writelane_b32 v253, s9, 48
	v_writelane_b32 v253, s6, 49
	s_add_u32 s2, s76, s2
	s_nop 0
	v_writelane_b32 v253, s7, 50
	v_writelane_b32 v253, s76, 51
	s_addc_u32 s3, s77, s3
	s_nop 0
	v_writelane_b32 v254, s89, 0
	v_writelane_b32 v254, s90, 1
	v_writelane_b32 v254, s91, 2
	v_writelane_b32 v254, s2, 3
	v_writelane_b32 v253, s77, 52
	v_writelane_b32 v253, s78, 53
	v_writelane_b32 v254, s3, 4
	s_lshl_b64 s[2:3], s[4:5], 9
	s_add_u32 s2, s94, s2
	s_addc_u32 s3, s95, s3
	s_add_u32 s2, s2, 0x9685000
	s_addc_u32 s3, s3, 0
	v_writelane_b32 v254, s2, 5
	s_lshl_b64 s[0:1], s[0:1], 9
	s_ashr_i32 s13, s12, 31
	v_writelane_b32 v254, s3, 6
	v_writelane_b32 v254, s0, 7
	v_writelane_b32 v253, s79, 54
	v_writelane_b32 v253, s80, 55
	v_writelane_b32 v254, s1, 8
	s_lshl_b32 s0, s18, 3
	v_writelane_b32 v254, s0, 9
	s_mul_i32 s0, s18, 12
	v_writelane_b32 v254, s0, 10
	s_add_i32 s0, s11, s59
	v_writelane_b32 v254, s0, 11
	s_lshl_b64 s[0:1], s[12:13], 11
	v_writelane_b32 v254, s0, 12
	v_writelane_b32 v253, s81, 56
	v_writelane_b32 v253, s82, 57
	v_writelane_b32 v254, s1, 13
	v_writelane_b32 v254, s12, 14
	s_lshl_b64 s[0:1], s[12:13], 12
	v_writelane_b32 v253, s83, 58
	v_writelane_b32 v254, s13, 15
	v_writelane_b32 v254, s0, 16
	v_writelane_b32 v253, s84, 59
	v_writelane_b32 v253, s85, 60
	v_writelane_b32 v254, s1, 17
	s_lshl_b32 s0, s18, 7
	v_writelane_b32 v254, s0, 18
	s_add_u32 s0, s94, 0x200
	s_addc_u32 s1, s95, 0
	v_writelane_b32 v254, s0, 19
	v_writelane_b32 v253, s86, 61
	v_writelane_b32 v253, s87, 62
	v_writelane_b32 v254, s1, 20
	s_add_u32 s0, s94, 4
	v_writelane_b32 v254, s0, 21
	s_addc_u32 s0, s95, 0
	v_writelane_b32 v254, s0, 22
	s_add_u32 s0, s94, 0xd885200
	s_addc_u32 s1, s95, 0
	v_writelane_b32 v254, s0, 23
	v_writelane_b32 v253, s88, 63
	s_nop 0
	v_writelane_b32 v254, s1, 24
	s_add_u32 s0, s94, 0xd089100
	s_addc_u32 s1, s95, 0
	v_writelane_b32 v254, s0, 25
	s_nop 1
	v_writelane_b32 v254, s1, 26
	s_add_u32 s0, s94, 0xf085200
	s_addc_u32 s1, s95, 0
	v_writelane_b32 v254, s0, 27
	s_nop 1
	v_writelane_b32 v254, s1, 28
	s_add_u32 s0, s94, 0xe889100
	s_addc_u32 s1, s95, 0
	v_writelane_b32 v254, s0, 29
	s_nop 1
	v_writelane_b32 v254, s1, 30
	s_add_u32 s0, s94, 0xdc85000
	v_writelane_b32 v254, s0, 31
	s_addc_u32 s0, s95, 0
	v_writelane_b32 v254, s0, 32
	s_add_u32 s0, s94, 0xd481100
	v_writelane_b32 v254, s0, 33
	s_addc_u32 s0, s95, 0
	v_writelane_b32 v254, s0, 34
	s_add_u32 s0, s94, 0x9805100
	v_writelane_b32 v254, s0, 35
	s_addc_u32 s0, s95, 0
	v_writelane_b32 v254, s0, 36
	s_add_u32 s0, s94, 0x9789000
	v_writelane_b32 v254, s0, 37
	s_addc_u32 s0, s95, 0
	v_writelane_b32 v254, s0, 38
	v_writelane_b32 v254, s11, 39
	s_add_i32 s0, s11, 0xffffe000
	v_writelane_b32 v254, s0, 40
	v_writelane_b32 v254, s62, 41
	s_nop 1
	v_writelane_b32 v254, s63, 42
	v_writelane_b32 v254, s50, 43
	s_nop 1
	v_writelane_b32 v254, s51, 44
	v_writelane_b32 v254, s18, 45
	s_nop 1
	v_writelane_b32 v254, s19, 46
	v_writelane_b32 v254, s22, 47
	s_nop 1
	v_writelane_b32 v254, s23, 48
	v_writelane_b32 v254, s14, 49
	s_nop 1
	v_writelane_b32 v254, s15, 50
	v_writelane_b32 v254, s16, 51
	s_nop 1
	v_writelane_b32 v254, s17, 52
	s_branch .LBB0_10

.LBB0_445:
	s_and_b32 s6, s34, 7
	s_lshl_b32 s6, s6, 4
	s_bfe_u32 s98, s34, 0x40004
	s_add_u32 s6, s6, s98
	s_lshr_b32 s12, s34, 9
	s_lshl_b32 s12, s12, 2
	s_bfe_u32 s98, s34, 0x10003
	s_add_u32 s12, s12, s98
	s_bfe_u32 s98, s34, 0x10008
	s_lshl_b32 s98, s98, 1
	s_add_u32 s12, s12, s98
	s_lshl_b32 s10, s6, 7
	v_add_u32_e32 v2, s10, v148
	v_ashrrev_i32_e32 v3, 31, v2
	v_lshl_add_u32 v4, s12, 7, v148
	v_lshlrev_b64 v[2:3], 11, v[2:3]
	v_ashrrev_i32_e32 v5, 31, v4
	v_lshlrev_b64 v[4:5], 11, v[4:5]
	v_lshl_add_u64 v[142:143], v[138:139], 0, v[2:3]
	v_mov_b32_e32 v2, 0
	v_lshl_add_u64 v[144:145], v[140:141], 0, v[4:5]
	s_mov_b32 s11, 0
	s_mov_b64 s[6:7], 0
	v_mov_b32_e32 v3, v2
	v_mov_b32_e32 v4, v2
	v_mov_b32_e32 v5, v2
	v_mov_b32_e32 v6, v2
	v_mov_b32_e32 v7, v2
	v_mov_b32_e32 v8, v2
	v_mov_b32_e32 v9, v2
	v_mov_b32_e32 v10, v2
	v_mov_b32_e32 v11, v2
	v_mov_b32_e32 v12, v2
	v_mov_b32_e32 v13, v2
	v_mov_b32_e32 v14, v2
	v_mov_b32_e32 v15, v2
	v_mov_b32_e32 v16, v2
	v_mov_b32_e32 v17, v2
	v_mov_b32_e32 v18, v2
	v_mov_b32_e32 v19, v2
	v_mov_b32_e32 v20, v2
	v_mov_b32_e32 v21, v2
	v_mov_b32_e32 v22, v2
	v_mov_b32_e32 v23, v2
	v_mov_b32_e32 v24, v2
	v_mov_b32_e32 v25, v2
	v_mov_b32_e32 v26, v2
	v_mov_b32_e32 v27, v2
	v_mov_b32_e32 v28, v2
	v_mov_b32_e32 v29, v2
	v_mov_b32_e32 v30, v2
	v_mov_b32_e32 v31, v2
	v_mov_b32_e32 v32, v2
	v_mov_b32_e32 v33, v2
	v_mov_b32_e32 v34, v2
	v_mov_b32_e32 v35, v2
	v_mov_b32_e32 v36, v2
	v_mov_b32_e32 v37, v2
	v_mov_b32_e32 v38, v2
	v_mov_b32_e32 v39, v2
	v_mov_b32_e32 v40, v2
	v_mov_b32_e32 v41, v2
	v_mov_b32_e32 v42, v2
	v_mov_b32_e32 v43, v2
	v_mov_b32_e32 v44, v2
	v_mov_b32_e32 v45, v2
	v_mov_b32_e32 v46, v2
	v_mov_b32_e32 v47, v2
	v_mov_b32_e32 v48, v2
	v_mov_b32_e32 v49, v2
	v_mov_b32_e32 v50, v2
	s_waitcnt lgkmcnt(0)
	v_mov_b32_e32 v51, v2
	v_mov_b32_e32 v52, v2
	v_mov_b32_e32 v53, v2
	v_mov_b32_e32 v54, v2
	v_mov_b32_e32 v55, v2
	v_mov_b32_e32 v56, v2
	v_mov_b32_e32 v57, v2
	v_mov_b32_e32 v58, v2
	v_mov_b32_e32 v59, v2
	v_mov_b32_e32 v60, v2
	v_mov_b32_e32 v61, v2
	v_mov_b32_e32 v62, v2
	v_mov_b32_e32 v63, v2
	v_mov_b32_e32 v64, v2
	v_mov_b32_e32 v65, v2
	s_waitcnt vmcnt(0)
	v_mov_b32_e32 v98, v70
	v_mov_b32_e32 v99, v71
	v_mov_b32_e32 v100, v72
	v_mov_b32_e32 v101, v73
	v_mov_b32_e32 v106, v74
	v_mov_b32_e32 v107, v75
	v_mov_b32_e32 v108, v76
	v_mov_b32_e32 v109, v77
	v_mov_b32_e32 v110, v82
	v_mov_b32_e32 v111, v83
	v_mov_b32_e32 v112, v84
	v_mov_b32_e32 v113, v85
	v_mov_b32_e32 v122, v90
	v_mov_b32_e32 v123, v91
	v_mov_b32_e32 v124, v92
	v_mov_b32_e32 v125, v93
	v_mov_b32_e32 v102, v66
	v_mov_b32_e32 v103, v67
	v_mov_b32_e32 v104, v68
	v_mov_b32_e32 v105, v69
	v_mov_b32_e32 v114, v78
	v_mov_b32_e32 v115, v79
	v_mov_b32_e32 v116, v80
	v_mov_b32_e32 v117, v81
	v_mov_b32_e32 v118, v86
	v_mov_b32_e32 v119, v87
	v_mov_b32_e32 v120, v88
	v_mov_b32_e32 v121, v89
	v_mov_b32_e32 v126, v94
	v_mov_b32_e32 v127, v95
	v_mov_b32_e32 v128, v96
	v_mov_b32_e32 v129, v97
	s_barrier
	ds_write_b128 v134, v[70:73]
	ds_write_b128 v134, v[66:69] offset:18432
	ds_write_b128 v134, v[74:77] offset:4608
	ds_write_b128 v134, v[78:81] offset:23040
	ds_write_b128 v134, v[82:85] offset:9216
	ds_write_b128 v134, v[86:89] offset:27648
	ds_write_b128 v134, v[90:93] offset:13824
	ds_write_b128 v134, v[94:97] offset:32256
	s_waitcnt lgkmcnt(0)
	s_barrier
	s_branch .LBB0_447

.LBB0_451:
	v_readlane_b32 s6, v254, 45
	s_add_i32 s34, s34, s6
	v_readlane_b32 s7, v254, 46
	s_cmpk_gt_i32 s34, 0x9ff
	s_cselect_b64 s[6:7], -1, 0
	s_and_b64 vcc, exec, s[6:7]
	s_cbranch_vccnz .LBB0_453
	s_lshr_b32 s8, s12, 2
	s_cmp_eq_u32 s8, 1
	s_cbranch_scc1 .LBB0_453
	s_sub_u32 s8, s12, 10
	s_cmp_lt_u32 s8, 4
	s_cbranch_scc1 .LBB0_453
	s_and_b32 s8, s34, 7
	s_lshl_b32 s8, s8, 4
	s_bfe_u32 s98, s34, 0x40004
	s_add_u32 s8, s8, s98
	s_lshr_b32 s9, s34, 9
	s_lshl_b32 s9, s9, 2
	s_bfe_u32 s98, s34, 0x10003
	s_add_u32 s9, s9, s98
	s_bfe_u32 s98, s34, 0x10008
	s_lshl_b32 s98, s98, 1
	s_add_u32 s9, s9, s98
	v_lshl_add_u32 v66, s8, 7, v148
	v_ashrrev_i32_e32 v67, 31, v66
	v_lshlrev_b64 v[66:67], 11, v[66:67]
	v_lshl_add_u64 v[90:91], v[130:131], 0, v[66:67]
	v_lshl_add_u32 v66, s9, 7, v148
	v_ashrrev_i32_e32 v67, 31, v66
	v_lshlrev_b64 v[66:67], 11, v[66:67]
	v_add_co_u32_e32 v74, vcc, 0x10000, v90
	v_lshl_add_u64 v[92:93], v[132:133], 0, v[66:67]
	s_nop 0
	v_addc_co_u32_e32 v75, vcc, 0, v91, vcc
	v_add_co_u32_e32 v78, vcc, 0x10000, v92
	global_load_dwordx4 v[70:73], v[90:91], off
	global_load_dwordx4 v[66:69], v[92:93], off
	v_addc_co_u32_e32 v79, vcc, 0, v93, vcc
	v_add_co_u32_e32 v82, vcc, 0x20000, v90
	global_load_dwordx4 v[74:77], v[74:75], off
	s_nop 0
	global_load_dwordx4 v[78:81], v[78:79], off
	v_addc_co_u32_e32 v83, vcc, 0, v91, vcc
	v_add_co_u32_e32 v86, vcc, 0x20000, v92
	s_nop 1
	v_addc_co_u32_e32 v87, vcc, 0, v93, vcc
	v_add_co_u32_e32 v90, vcc, 0x30000, v90
	global_load_dwordx4 v[82:85], v[82:83], off
	s_nop 0
	global_load_dwordx4 v[86:89], v[86:87], off
	v_addc_co_u32_e32 v91, vcc, 0, v91, vcc
	v_add_co_u32_e32 v94, vcc, 0x30000, v92
	s_nop 1
	v_addc_co_u32_e32 v95, vcc, 0, v93, vcc
	global_load_dwordx4 v[90:93], v[90:91], off
	s_nop 0
	global_load_dwordx4 v[94:97], v[94:95], off

.LBB0_470:
	s_andn2_b64 vcc, exec, s[12:13]
	s_cbranch_vccnz .LBB0_488
	s_cmp_eq_u32 s19, 5
	s_cselect_b64 s[14:15], -1, 0
	v_readlane_b32 s72, v250, 18
	s_and_b64 s[10:11], s[14:15], exec
	v_readlane_b32 s76, v250, 22
	v_readlane_b32 s78, v250, 24
	v_readlane_b32 s77, v250, 23
	v_readlane_b32 s79, v250, 25
	s_cselect_b32 s11, s76, s78
	v_ashrrev_i32_e32 v27, 31, v26
	s_cselect_b32 s10, s77, s79
	s_add_u32 s12, s11, s2
	v_lshl_add_u64 v[2:3], v[26:27], 4, s[0:1]
	s_addc_u32 s13, s10, s3
	v_or_b32_e32 v2, v2, v25
	v_readlane_b32 s10, v251, 55
	v_lshlrev_b64 v[2:3], 16, v[2:3]
	v_readlane_b32 s11, v251, 56
	v_lshlrev_b32_e32 v4, 8, v0
	v_mov_b32_e32 v5, v1
	v_lshl_add_u64 v[2:3], s[10:11], 0, v[2:3]
	v_lshl_add_u64 v[34:35], v[2:3], 0, v[4:5]
	ds_read2_b32 v[14:15], v155 offset0:6 offset1:7
	ds_read2_b32 v[16:17], v155 offset0:14 offset1:15
	ds_read2_b32 v[22:23], v155 offset0:22 offset1:23
	ds_read2_b32 v[50:51], v155 offset0:16 offset1:17
	ds_read2_b32 v[48:49], v155 offset0:18 offset1:19
	s_waitcnt vmcnt(5)
	ds_read2_b32 v[108:109], v155 offset1:1
	ds_read2_b32 v[18:19], v155 offset0:8 offset1:9
	ds_read2_b32 v[38:39], v155 offset0:24 offset1:25
	ds_read2_b32 v[40:41], v155 offset0:26 offset1:27
	ds_read2_b32 v[42:43], v155 offset0:28 offset1:29
	ds_read2_b32 v[46:47], v155 offset0:20 offset1:21
	ds_read2_b32 v[44:45], v155 offset0:30 offset1:31
	global_load_dwordx4 v[2:5], v1, s[12:13] offset:16
	global_load_dwordx4 v[6:9], v1, s[12:13] offset:48
	global_load_dwordx4 v[10:13], v1, s[12:13] offset:32
	global_load_dwordx4 v[104:107], v1, s[12:13]
	global_load_dwordx4 v[124:127], v1, s[12:13]
	global_load_dwordx4 v[142:145], v1, s[12:13] offset:16
	global_load_dwordx4 v[158:161], v1, s[12:13] offset:32
	global_load_dwordx4 v[162:165], v1, s[12:13] offset:48
	global_load_dwordx4 v[166:169], v1, s[12:13] offset:64
	global_load_dwordx4 v[170:173], v1, s[12:13] offset:80
	global_load_dwordx4 v[174:177], v1, s[12:13] offset:96
	global_load_dwordx4 v[178:181], v1, s[12:13] offset:112
	v_lshrrev_b32_e32 v248, 6, v0
	v_lshlrev_b32_e32 v248, 6, v248
	s_and_saveexec_b64 s[16:17], s[42:43]
	global_load_dwordx4 v[182:185], v248, s[62:63]
	global_load_dwordx4 v[186:189], v248, s[62:63] offset:16
	global_load_dwordx4 v[190:193], v248, s[62:63] offset:32
	global_load_dwordx4 v[194:197], v248, s[62:63] offset:48
	global_load_dwordx4 v[208:211], v[136:137], off
	global_load_dwordx4 v[214:217], v[136:137], off offset:16
	global_load_dwordx4 v[228:231], v[136:137], off offset:32
	global_load_dwordx4 v[244:247], v[136:137], off offset:48
	s_or_b64 exec, exec, s[16:17]
	s_and_b64 vcc, exec, s[6:7]
	s_cbranch_vccnz .Lpje_b_nopf
	s_and_b32 s8, s34, 7
	s_lshl_b32 s8, s8, 4
	s_bfe_u32 s98, s34, 0x40004
	s_add_u32 s8, s8, s98
	s_lshr_b32 s9, s34, 9
	s_lshl_b32 s9, s9, 2
	s_bfe_u32 s98, s34, 0x10003
	s_add_u32 s9, s9, s98
	s_bfe_u32 s98, s34, 0x10008
	s_lshl_b32 s98, s98, 1
	s_add_u32 s9, s9, s98
	v_lshl_add_u32 v66, s8, 7, v148
	v_ashrrev_i32_e32 v67, 31, v66
	v_lshlrev_b64 v[66:67], 11, v[66:67]
	v_lshl_add_u64 v[90:91], v[130:131], 0, v[66:67]
	v_lshl_add_u32 v66, s9, 7, v148
	v_ashrrev_i32_e32 v67, 31, v66
	v_lshlrev_b64 v[66:67], 11, v[66:67]
	v_add_co_u32_e32 v74, vcc, 0x10000, v90
	v_lshl_add_u64 v[92:93], v[132:133], 0, v[66:67]
	s_nop 0
	v_addc_co_u32_e32 v75, vcc, 0, v91, vcc
	v_add_co_u32_e32 v78, vcc, 0x10000, v92
	global_load_dwordx4 v[70:73], v[90:91], off
	global_load_dwordx4 v[66:69], v[92:93], off
	v_addc_co_u32_e32 v79, vcc, 0, v93, vcc
	v_add_co_u32_e32 v82, vcc, 0x20000, v90
	global_load_dwordx4 v[74:77], v[74:75], off
	s_nop 0
	global_load_dwordx4 v[78:81], v[78:79], off
	v_addc_co_u32_e32 v83, vcc, 0, v91, vcc
	v_add_co_u32_e32 v86, vcc, 0x20000, v92
	s_nop 1
	v_addc_co_u32_e32 v87, vcc, 0, v93, vcc
	v_add_co_u32_e32 v90, vcc, 0x30000, v90
	global_load_dwordx4 v[82:85], v[82:83], off
	s_nop 0
	global_load_dwordx4 v[86:89], v[86:87], off
	v_addc_co_u32_e32 v91, vcc, 0, v91, vcc
	v_add_co_u32_e32 v94, vcc, 0x30000, v92
	s_nop 1
	v_addc_co_u32_e32 v95, vcc, 0, v93, vcc
	global_load_dwordx4 v[90:93], v[90:91], off
	s_nop 0
	global_load_dwordx4 v[94:97], v[94:95], off

.LBB0_507:
	s_and_b64 vcc, exec, s[10:11]
	s_cbranch_vccz .LBB0_525
	s_cmp_eq_u32 s19, 3
	v_readlane_b32 s72, v252, 2
	s_cselect_b64 s[10:11], -1, 0
	s_cmp_eq_u32 s19, 2
	v_readlane_b32 s86, v252, 16
	v_readlane_b32 s16, v250, 18
	v_readlane_b32 s87, v252, 17
	v_readlane_b32 s17, v250, 19
	s_cselect_b32 s12, s86, s16
	s_mov_b32 s14, 0xc885100
	s_cselect_b32 s13, s87, s17
	s_cselect_b32 s14, s14, 0xd085100
	s_add_u32 s12, s12, s4
	s_addc_u32 s13, s13, s5
	ds_read2_b32 v[34:35], v155 offset1:1
	ds_read2_b32 v[36:37], v155 offset0:2 offset1:3
	ds_read2_b32 v[38:39], v155 offset0:4 offset1:5
	ds_read2_b32 v[40:41], v155 offset0:6 offset1:7
	ds_read2_b32 v[42:43], v155 offset0:8 offset1:9
	ds_read2_b32 v[44:45], v155 offset0:10 offset1:11
	ds_read2_b32 v[46:47], v155 offset0:12 offset1:13
	ds_read2_b32 v[48:49], v155 offset0:14 offset1:15
	ds_read2_b32 v[50:51], v155 offset0:16 offset1:17
	ds_read2_b32 v[52:53], v155 offset0:18 offset1:19
	ds_read2_b32 v[54:55], v155 offset0:20 offset1:21
	ds_read2_b32 v[56:57], v155 offset0:22 offset1:23
	ds_read2_b32 v[58:59], v155 offset0:24 offset1:25
	ds_read2_b32 v[60:61], v155 offset0:26 offset1:27
	ds_read2_b32 v[62:63], v155 offset0:28 offset1:29
	ds_read2_b32 v[64:65], v155 offset0:30 offset1:31
	ds_read2_b32 v[98:99], v155 offset0:32 offset1:33
	ds_read2_b32 v[100:101], v155 offset0:34 offset1:35
	ds_read2_b32 v[102:103], v155 offset0:36 offset1:37
	ds_read2_b32 v[104:105], v155 offset0:38 offset1:39
	ds_read2_b32 v[106:107], v155 offset0:40 offset1:41
	ds_read2_b32 v[108:109], v155 offset0:42 offset1:43
	ds_read2_b32 v[110:111], v155 offset0:44 offset1:45
	ds_read2_b32 v[112:113], v155 offset0:46 offset1:47
	ds_read2_b32 v[114:115], v155 offset0:48 offset1:49
	ds_read2_b32 v[116:117], v155 offset0:50 offset1:51
	ds_read2_b32 v[118:119], v155 offset0:52 offset1:53
	ds_read2_b32 v[120:121], v155 offset0:54 offset1:55
	ds_read2_b32 v[122:123], v155 offset0:56 offset1:57
	ds_read2_b32 v[124:125], v155 offset0:58 offset1:59
	ds_read2_b32 v[126:127], v155 offset0:60 offset1:61
	ds_read2_b32 v[128:129], v155 offset0:62 offset1:63
	global_load_dwordx4 v[158:161], v1, s[12:13]
	global_load_dwordx4 v[162:165], v1, s[12:13] offset:16
	global_load_dwordx4 v[166:169], v1, s[12:13] offset:32
	global_load_dwordx4 v[170:173], v1, s[12:13] offset:48
	global_load_dwordx4 v[174:177], v1, s[12:13] offset:64
	global_load_dwordx4 v[178:181], v1, s[12:13] offset:80
	global_load_dwordx4 v[182:185], v1, s[12:13] offset:96
	global_load_dwordx4 v[186:189], v1, s[12:13] offset:112
	global_load_dwordx4 v[190:193], v1, s[12:13] offset:128
	global_load_dwordx4 v[194:197], v1, s[12:13] offset:144
	global_load_dwordx4 v[2:5], v1, s[12:13] offset:160
	global_load_dwordx4 v[6:9], v1, s[12:13] offset:176
	global_load_dwordx4 v[10:13], v1, s[12:13] offset:192
	global_load_dwordx4 v[14:17], v1, s[12:13] offset:208
	global_load_dwordx4 v[18:21], v1, s[12:13] offset:224
	global_load_dwordx4 v[28:31], v1, s[12:13] offset:240
	s_and_b64 vcc, exec, s[6:7]
	s_cbranch_vccnz .Lpje_d_nopf
	s_and_b32 s8, s34, 7
	s_lshl_b32 s8, s8, 4
	s_bfe_u32 s98, s34, 0x40004
	s_add_u32 s8, s8, s98
	s_lshr_b32 s9, s34, 9
	s_lshl_b32 s9, s9, 2
	s_bfe_u32 s98, s34, 0x10003
	s_add_u32 s9, s9, s98
	s_bfe_u32 s98, s34, 0x10008
	s_lshl_b32 s98, s98, 1
	s_add_u32 s9, s9, s98
	v_lshl_add_u32 v66, s8, 7, v148
	v_ashrrev_i32_e32 v67, 31, v66
	v_lshlrev_b64 v[66:67], 11, v[66:67]
	v_lshl_add_u64 v[90:91], v[130:131], 0, v[66:67]
	v_lshl_add_u32 v66, s9, 7, v148
	v_ashrrev_i32_e32 v67, 31, v66
	v_lshlrev_b64 v[66:67], 11, v[66:67]
	v_add_co_u32_e32 v74, vcc, 0x10000, v90
	v_lshl_add_u64 v[92:93], v[132:133], 0, v[66:67]
	s_nop 0
	v_addc_co_u32_e32 v75, vcc, 0, v91, vcc
	v_add_co_u32_e32 v78, vcc, 0x10000, v92
	global_load_dwordx4 v[70:73], v[90:91], off
	global_load_dwordx4 v[66:69], v[92:93], off
	v_addc_co_u32_e32 v79, vcc, 0, v93, vcc
	v_add_co_u32_e32 v82, vcc, 0x20000, v90
	global_load_dwordx4 v[74:77], v[74:75], off
	s_nop 0
	global_load_dwordx4 v[78:81], v[78:79], off
	v_addc_co_u32_e32 v83, vcc, 0, v91, vcc
	v_add_co_u32_e32 v86, vcc, 0x20000, v92
	s_nop 1
	v_addc_co_u32_e32 v87, vcc, 0, v93, vcc
	v_add_co_u32_e32 v90, vcc, 0x30000, v90
	global_load_dwordx4 v[82:85], v[82:83], off
	s_nop 0
	global_load_dwordx4 v[86:89], v[86:87], off
	v_addc_co_u32_e32 v91, vcc, 0, v91, vcc
	v_add_co_u32_e32 v94, vcc, 0x30000, v92
	s_nop 1
	v_addc_co_u32_e32 v95, vcc, 0, v93, vcc
	global_load_dwordx4 v[90:93], v[90:91], off
	s_nop 0
	global_load_dwordx4 v[94:97], v[94:95], off
